# attention loop 1: waves 4-7 run a loop copy with the first-half exps after the K Q^T MFMAs (complementary phases for the two waves of a SIMD)
# speedup vs baseline: 1.0017x; 1.0006x over previous
; #define AT_LOADK(t_) do { const size_t kb_ = (size_t)(t_) * 64; rk0 = *(const u32x4*)(Kh + (kb_ + kkey0) * 96 + kpart0 * 8); if (tid < 256) rk1 = *(const u32x4*)(Kh + (kb_ + kkey1) * 96 + kpart1 * 8); } while (0)
; #define AT_LOADV(t_) do { rv = *(const u32x4*)(Vh + (size_t)vdv * S + (size_t)(t_) * 64 + vpart * 8); } while (0)
; #define AT_WRITEK(t_) do { LAS unsigned char* Ks_ = lds + ((t_) & 1) * AT_KT; *(LAS u32x4*)(Ks_ + kkey0 * AT_KROW + kpart0 * 16) = rk0; if (tid < 256) *(LAS u32x4*)(Ks_ + kkey1 * AT_KROW + kpart1 * 16) = rk1; } while (0)
; DI void attn_unit(int wv, int h, int qb, const bf16_t* QB, const bf16_t* KB, const bf16_t* VT, bf16_t* MIX, LAS unsigned char* lds) {
;     ...
;     f32x16 pA0, pA1, pB0 = {}, pB1 = {}; float mA = 0.f, mB = 0.f;
;     AT_LOADK(0); AT_WRITEK(0);
;     __syncthreads();
;     AT_LOADK(1); AT_LOADV(0);
;     AT_QK(pA0, pA1, 0);
;     int t = 0;
.LBB0_799:
	s_or_b64 exec, exec, s[0:1]
	v_mad_u32_u24 v2, v22, s37, 0
	v_add_u32_e32 v201, v2, v0
	ds_read_b128 v[2:5], v201
	ds_read_b128 v[12:15], v201 offset:32
	s_lshl_b64 s[40:41], s[88:89], 21
	v_readlane_b32 s0, v240, 7
	v_ashrrev_i32_e32 v38, 3, v9
	s_waitcnt lgkmcnt(1)
	v_mfma_f32_32x32x16_bf16 v[50:65], v[2:5], v[114:117], 0
	ds_read_b128 v[2:5], v201 offset:6656
	ds_read_b128 v[26:29], v201 offset:6688
	s_add_u32 s80, s0, s40
	v_ashrrev_i32_e32 v39, 31, v38
	v_readlane_b32 s0, v240, 8
	s_addc_u32 s81, s0, s41
	v_lshlrev_b64 v[40:41], 15, v[38:39]
	v_lshlrev_b32_e32 v0, 4, v8
	s_waitcnt lgkmcnt(1)
	v_mfma_f32_32x32x16_bf16 v[66:81], v[2:5], v[114:117], 0
	v_lshl_add_u64 v[2:3], s[80:81], 0, v[40:41]
	v_and_b32_e32 v158, 0x70, v0
	v_mov_b32_e32 v159, v1
	v_lshl_add_u64 v[2:3], v[2:3], 0, v[158:159]
	global_load_dwordx4 v[146:149], v[2:3], off
	ds_read_b128 v[2:5], v201 offset:64
	ds_read_b128 v[6:9], v201 offset:96
	v_mad_i64_i32 v[42:43], s[0:1], v10, s34, 0
	v_mfma_f32_32x32x16_bf16 v[50:65], v[12:15], v[118:121], v[50:65]
	ds_read_b128 v[10:13], v201 offset:6752
	s_mov_b32 s12, 0
	s_mov_b32 s13, s12
	v_add_u32_e32 v159, 0, v24
	v_mov_b64_e32 v[24:25], s[70:71]
	v_lshlrev_b32_e32 v0, 3, v178
	s_mov_b32 s14, s12
	s_waitcnt lgkmcnt(2)
	v_mfma_f32_32x32x16_bf16 v[50:65], v[2:5], v[122:125], v[50:65]
	ds_read_b128 v[2:5], v201 offset:6720
	s_mov_b32 s15, s12
	s_mov_b32 s16, s12
	s_mov_b32 s17, s12
	s_mov_b32 s18, s12
	s_mov_b32 s19, s12
	s_mov_b32 s20, s12
	v_mfma_f32_32x32x16_bf16 v[66:81], v[26:29], v[118:121], v[66:81]
	ds_read_b128 v[26:29], v201 offset:128
	ds_read_b128 v[30:33], v201 offset:6784
	ds_read_b128 v[34:37], v201 offset:160
	ds_read_b128 v[82:85], v201 offset:6816
	s_mov_b32 s21, s12
	s_mov_b32 s22, s12
	s_mov_b32 s23, s12
	s_mov_b32 s24, s12
	s_waitcnt lgkmcnt(4)
	v_mfma_f32_32x32x16_bf16 v[66:81], v[2:5], v[122:125], v[66:81]
	s_mov_b32 s25, s12
	s_mov_b32 s26, s12
	s_mov_b32 s27, s12
	v_lshl_add_u64 v[160:161], s[40:41], 0, v[40:41]
	v_or_b32_e32 v160, v160, v158
	s_lshl_b32 s29, s10, 2
	s_mov_b32 s89, 3
	v_mfma_f32_32x32x16_bf16 v[50:65], v[6:9], v[126:129], v[50:65]
	v_or_b32_e32 v156, 0x100, v160
	v_mov_b32_e32 v157, v161
	v_mov_b32_e32 v205, 0
	s_mov_b32 s90, 5
	v_mov_b32_e32 v203, 0
	v_mfma_f32_32x32x16_bf16 v[66:81], v[10:13], v[126:129], v[66:81]
	v_mov_b64_e32 v[2:3], s[12:13]
	v_mov_b64_e32 v[16:17], s[26:27]
	v_mov_b64_e32 v[4:5], s[14:15]
	v_mov_b64_e32 v[6:7], s[16:17]
	v_mov_b64_e32 v[8:9], s[18:19]
	v_mov_b64_e32 v[10:11], s[20:21]
	v_mov_b64_e32 v[12:13], s[22:23]
	s_waitcnt lgkmcnt(3)
	v_mfma_f32_32x32x16_bf16 v[50:65], v[26:29], v[130:133], v[50:65]
	v_mul_u32_u24_e32 v27, 0x88, v22
	v_mad_i64_i32 v[22:23], s[0:1], v23, s34, v[24:25]
	v_add_u32_e32 v26, 0, v0
	v_lshl_add_u64 v[150:151], v[20:21], 1, v[22:23]
	v_lshl_add_u64 v[20:21], s[70:71], 0, v[42:43]
	v_mov_b64_e32 v[14:15], s[24:25]
	s_waitcnt lgkmcnt(2)
	v_mfma_f32_32x32x16_bf16 v[66:81], v[30:33], v[130:133], v[66:81]
	v_mul_lo_u32 v0, v38, s38
	v_lshl_add_u64 v[152:153], v[18:19], 1, v[20:21]
	v_add_u32_e32 v179, v26, v27
	v_mov_b64_e32 v[32:33], v[16:17]
	v_add_u32_e32 v0, 0, v0
	v_mov_b64_e32 v[30:31], v[14:15]
	v_mov_b64_e32 v[28:29], v[12:13]
	s_waitcnt lgkmcnt(1)
	v_mfma_f32_32x32x16_bf16 v[50:65], v[34:37], v[134:137], v[50:65]
	v_mov_b64_e32 v[48:49], v[16:17]
	v_mov_b64_e32 v[26:27], v[10:11]
	v_mov_b64_e32 v[24:25], v[8:9]
	v_mov_b64_e32 v[22:23], v[6:7]
	v_mov_b64_e32 v[20:21], v[4:5]
	v_mov_b64_e32 v[18:19], v[2:3]
	v_mov_b64_e32 v[46:47], v[14:15]
	s_waitcnt lgkmcnt(0)
	v_mfma_f32_32x32x16_bf16 v[66:81], v[82:85], v[134:137], v[66:81]
	v_mov_b64_e32 v[44:45], v[12:13]
	v_mov_b64_e32 v[42:43], v[10:11]
	v_mov_b64_e32 v[40:41], v[8:9]
	v_mov_b64_e32 v[38:39], v[6:7]
	v_mov_b64_e32 v[36:37], v[4:5]
	v_mov_b64_e32 v[34:35], v[2:3]
	s_add_u32 s52, s94, 0xad71000
	s_addc_u32 s53, s95, 0
	s_add_u32 s54, s94, 0xad74000
	s_addc_u32 s55, s95, 0
	s_add_u32 s56, s94, 0xc56b000
	s_addc_u32 s57, s95, 0
	v_add3_u32 v202, v0, v158, s33
	v_add3_u32 v208, v0, v158, s4
	v_add_u32_e32 v206, 0x6800, v179
	v_add_u32_e32 v207, 0x7800, v179
	v_add_u32_e32 v209, 0x8800, v179
	v_add_u32_e32 v241, v159, v191
	s_waitcnt vmcnt(1)
	ds_write_b128 v190, v[142:145] offset:13312
	s_and_saveexec_b64 s[8:9], s[6:7]
	s_cmp_eq_u64 s[6:7], 0
	s_cbranch_scc1 .Lw47_b801
	s_branch .LBB0_801

.Lw47_b813:
	ds_read_b128 v[98:101], v201 offset:13312
	ds_read_b128 v[102:105], v201 offset:13344
	s_waitcnt lgkmcnt(0)
	v_mfma_f32_32x32x16_bf16 v[82:97], v[98:101], v[114:117], v[34:49]
	v_mfma_f32_32x32x16_bf16 v[82:97], v[102:105], v[118:121], v[82:97]
	ds_read_b128 v[98:101], v201 offset:13376
	ds_read_b128 v[102:105], v201 offset:13408
	s_waitcnt lgkmcnt(0)
	v_mfma_f32_32x32x16_bf16 v[82:97], v[98:101], v[122:125], v[82:97]
	v_mfma_f32_32x32x16_bf16 v[82:97], v[102:105], v[126:129], v[82:97]
	ds_read_b128 v[98:101], v201 offset:13440
	ds_read_b128 v[102:105], v201 offset:13472
	ds_read_b128 v[170:173], v201 offset:19968
	ds_read_b128 v[174:177], v201 offset:20000
	s_waitcnt lgkmcnt(2)
	v_mfma_f32_32x32x16_bf16 v[82:97], v[98:101], v[130:133], v[82:97]
	v_mfma_f32_32x32x16_bf16 v[82:97], v[102:105], v[134:137], v[82:97]
	s_waitcnt lgkmcnt(0)
	v_mfma_f32_32x32x16_bf16 v[98:113], v[170:173], v[114:117], v[34:49]
	v_mfma_f32_32x32x16_bf16 v[98:113], v[174:177], v[118:121], v[98:113]
	ds_read_b128 v[170:173], v201 offset:20032
	ds_read_b128 v[174:177], v201 offset:20064
	s_waitcnt lgkmcnt(0)
	v_mfma_f32_32x32x16_bf16 v[98:113], v[170:173], v[122:125], v[98:113]
	v_mfma_f32_32x32x16_bf16 v[98:113], v[174:177], v[126:129], v[98:113]
	ds_read_b128 v[170:173], v201 offset:20096
	ds_read_b128 v[174:177], v201 offset:20128
	ds_read2_b64 v[180:183], v206 offset0:4 offset1:6
	s_waitcnt lgkmcnt(2)
	v_mfma_f32_32x32x16_bf16 v[98:113], v[170:173], v[130:133], v[98:113]
	ds_read2_b64 v[170:173], v206 offset1:2
	s_waitcnt lgkmcnt(2)
	v_mfma_f32_32x32x16_bf16 v[98:113], v[174:177], v[134:137], v[98:113]
	v_exp_f32_e32 v50, v50
	v_exp_f32_e32 v51, v51
	v_exp_f32_e32 v52, v52
	v_exp_f32_e32 v53, v53
	v_exp_f32_e32 v54, v54
	v_exp_f32_e32 v55, v55
	v_exp_f32_e32 v56, v56
	v_exp_f32_e32 v57, v57
	v_cvt_pk_bf16_f32 v174, v50, v51
	v_cvt_pk_bf16_f32 v175, v52, v53
	v_cvt_pk_bf16_f32 v176, v54, v55
	v_cvt_pk_bf16_f32 v177, v56, v57
	s_waitcnt lgkmcnt(0)
	s_nop 0
	v_mfma_f32_32x32x16_bf16 v[2:17], v[170:173], v[174:177], v[2:17]
	ds_read2_b64 v[170:173], v207 offset0:32 offset1:34
	s_waitcnt lgkmcnt(0)
	v_mfma_f32_32x32x16_bf16 v[18:33], v[170:173], v[174:177], v[18:33]
	ds_read2_b64 v[174:177], v207 offset0:36 offset1:38
	v_exp_f32_e32 v58, v58
	v_exp_f32_e32 v59, v59
	v_exp_f32_e32 v60, v60
	v_exp_f32_e32 v61, v61
	v_exp_f32_e32 v62, v62
	v_exp_f32_e32 v63, v63
	v_exp_f32_e32 v64, v64
	v_exp_f32_e32 v65, v65
	v_cvt_pk_bf16_f32 v170, v58, v59
	v_cvt_pk_bf16_f32 v171, v60, v61
	v_cvt_pk_bf16_f32 v172, v62, v63
	v_cvt_pk_bf16_f32 v173, v64, v65
	s_nop 1
	v_mfma_f32_32x32x16_bf16 v[2:17], v[180:183], v[170:173], v[2:17]
	ds_read2_b64 v[180:183], v206 offset0:8 offset1:10
	s_waitcnt lgkmcnt(1)
	v_mfma_f32_32x32x16_bf16 v[18:33], v[174:177], v[170:173], v[18:33]
	ds_read2_b64 v[174:177], v207 offset0:40 offset1:42
	v_exp_f32_e32 v66, v66
	v_exp_f32_e32 v67, v67
	v_exp_f32_e32 v68, v68
	v_exp_f32_e32 v69, v69
	v_exp_f32_e32 v70, v70
	v_exp_f32_e32 v71, v71
	v_exp_f32_e32 v72, v72
	v_exp_f32_e32 v73, v73
	v_cvt_pk_bf16_f32 v170, v66, v67
	v_cvt_pk_bf16_f32 v171, v68, v69
	v_cvt_pk_bf16_f32 v172, v70, v71
	v_cvt_pk_bf16_f32 v173, v72, v73
	s_waitcnt lgkmcnt(1)
	s_nop 0
	v_mfma_f32_32x32x16_bf16 v[2:17], v[180:183], v[170:173], v[2:17]
	ds_read2_b64 v[180:183], v206 offset0:12 offset1:14
	s_waitcnt lgkmcnt(1)
	v_mfma_f32_32x32x16_bf16 v[18:33], v[174:177], v[170:173], v[18:33]
	ds_read2_b64 v[174:177], v207 offset0:44 offset1:46
	v_exp_f32_e32 v74, v74
	v_exp_f32_e32 v75, v75
	v_exp_f32_e32 v76, v76
	v_exp_f32_e32 v77, v77
	v_exp_f32_e32 v78, v78
	v_exp_f32_e32 v79, v79
	v_exp_f32_e32 v80, v80
	v_exp_f32_e32 v81, v81
	v_cvt_pk_bf16_f32 v170, v74, v75
	v_cvt_pk_bf16_f32 v171, v76, v77
	v_cvt_pk_bf16_f32 v172, v78, v79
	v_cvt_pk_bf16_f32 v173, v80, v81
	s_waitcnt vmcnt(1)
	ds_write_b128 v190, v[142:145]
	s_waitcnt lgkmcnt(2)
	v_mfma_f32_32x32x16_bf16 v[2:17], v[180:183], v[170:173], v[2:17]
	s_waitcnt lgkmcnt(1)
	v_mfma_f32_32x32x16_bf16 v[18:33], v[174:177], v[170:173], v[18:33]
	s_and_saveexec_b64 s[8:9], s[6:7]
	ds_write_b128 v241, v[138:141]
	s_or_b64 exec, exec, s[8:9]
	s_waitcnt vmcnt(0)
	ds_write2_b64 v208, v[146:147], v[148:149] offset1:1
	s_waitcnt lgkmcnt(0)
	s_barrier
	global_load_dwordx4 v[142:145], v152, s[54:55]
	s_and_saveexec_b64 s[8:9], s[6:7]
	s_cbranch_execz .Lw47_b817
	global_load_dwordx4 v[138:141], v150, s[54:55]

.Lw47_b820:
	ds_read_b128 v[66:69], v201
	ds_read_b128 v[70:73], v201 offset:32
	v_exp_f32_e32 v163, v86
	v_exp_f32_e32 v162, v87
	s_waitcnt lgkmcnt(0)
	v_mfma_f32_32x32x16_bf16 v[50:65], v[66:69], v[114:117], v[34:49]
	v_exp_f32_e32 v82, v82
	v_exp_f32_e32 v83, v83
	v_exp_f32_e32 v84, v84
	v_exp_f32_e32 v85, v85
	v_exp_f32_e32 v87, v104
	v_exp_f32_e32 v86, v105
	v_mfma_f32_32x32x16_bf16 v[50:65], v[70:73], v[118:121], v[50:65]
	ds_read_b128 v[66:69], v201 offset:64
	ds_read_b128 v[70:73], v201 offset:96
	v_exp_f32_e32 v175, v102
	v_exp_f32_e32 v174, v103
	v_cvt_pk_bf16_f32 v102, v82, v83
	v_cvt_pk_bf16_f32 v103, v84, v85
	v_cvt_pk_bf16_f32 v104, v163, v162
	v_exp_f32_e32 v177, v96
	s_waitcnt lgkmcnt(1)
	v_mfma_f32_32x32x16_bf16 v[50:65], v[66:69], v[122:125], v[50:65]
	ds_read_b128 v[66:69], v201 offset:128
	v_exp_f32_e32 v176, v97
	v_exp_f32_e32 v98, v98
	v_exp_f32_e32 v99, v99
	v_exp_f32_e32 v100, v100
	v_exp_f32_e32 v101, v101
	v_add_f32_e32 v181, v98, v82
	s_waitcnt lgkmcnt(1)
	v_mfma_f32_32x32x16_bf16 v[50:65], v[70:73], v[126:129], v[50:65]
	ds_read_b128 v[166:169], v201 offset:6656
	ds_read_b128 v[170:173], v201 offset:6688
	ds_read_b128 v[182:185], v201 offset:6720
	ds_read_b128 v[186:189], v201 offset:6752
	ds_read_b128 v[70:73], v201 offset:160
	ds_read_b128 v[210:213], v201 offset:6784
	ds_read_b128 v[214:217], v201 offset:6816
	v_add_f32_e32 v203, v99, v83
	v_add_f32_e32 v181, 0, v181
	v_add_f32_e32 v228, v100, v84
	v_add_f32_e32 v181, v203, v181
	v_add_f32_e32 v229, v101, v85
	s_waitcnt lgkmcnt(7)
	v_mfma_f32_32x32x16_bf16 v[50:65], v[66:69], v[130:133], v[50:65]
	v_add_f32_e64 v218, v174, v162
	v_add_f32_e64 v219, v175, v163
	s_add_i32 s12, s12, 2
	s_add_i32 s0, s90, 2
	s_add_i32 s1, s89, 2
	s_waitcnt lgkmcnt(2)
	v_mfma_f32_32x32x16_bf16 v[50:65], v[70:73], v[134:137], v[50:65]
	s_cmp_ge_u32 s12, s29
	v_mfma_f32_32x32x16_bf16 v[66:81], v[166:169], v[114:117], v[34:49]
	v_exp_f32_e32 v167, v88
	v_exp_f32_e32 v166, v89
	v_exp_f32_e32 v169, v90
	v_exp_f32_e32 v89, v106
	v_exp_f32_e32 v168, v91
	v_exp_f32_e32 v88, v107
	v_exp_f32_e32 v91, v108
	v_mfma_f32_32x32x16_bf16 v[66:81], v[170:173], v[118:121], v[66:81]
	v_exp_f32_e32 v90, v109
	ds_read2_b64 v[106:109], v209 offset0:64 offset1:66
	v_exp_f32_e32 v171, v92
	v_exp_f32_e32 v170, v93
	v_exp_f32_e32 v93, v110
	v_exp_f32_e32 v92, v111
	v_mfma_f32_32x32x16_bf16 v[66:81], v[182:185], v[122:125], v[66:81]
	v_cvt_pk_bf16_f32 v105, v167, v166
	v_exp_f32_e32 v173, v94
	v_exp_f32_e32 v172, v95
	v_exp_f32_e32 v95, v112
	v_exp_f32_e32 v94, v113
	ds_read2_b64 v[110:113], v209 offset0:68 offset1:70
	v_add_f32_e32 v220, v86, v166
	v_add_f32_e32 v221, v87, v167
	v_mfma_f32_32x32x16_bf16 v[66:81], v[186:189], v[126:129], v[66:81]
	v_add_f32_e32 v222, v88, v168
	v_add_f32_e32 v223, v89, v169
	v_add_f32_e32 v96, v90, v170
	v_add_f32_e32 v97, v91, v171
	v_add_f32_e32 v224, v92, v172
	v_add_f32_e32 v225, v93, v173
	v_add_f32_e32 v226, v94, v176
	v_add_f32_e32 v227, v95, v177
	s_waitcnt lgkmcnt(3)
	v_mfma_f32_32x32x16_bf16 v[66:81], v[210:213], v[130:133], v[66:81]
	v_add_u32_e32 v210, 0x9800, v179
	ds_read2_b64 v[182:185], v210 offset0:96 offset1:98
	s_nop 0
	v_cvt_pk_bf16_f32 v212, v89, v88
	s_waitcnt lgkmcnt(2)
	v_mfma_f32_32x32x16_bf16 v[2:17], v[106:109], v[102:105], v[2:17]
	v_cvt_pk_bf16_f32 v106, v169, v168
	v_cvt_pk_bf16_f32 v107, v171, v170
	v_cvt_pk_bf16_f32 v108, v173, v172
	v_cvt_pk_bf16_f32 v109, v177, v176
	s_waitcnt lgkmcnt(0)
	v_mfma_f32_32x32x16_bf16 v[18:33], v[182:185], v[102:105], v[18:33]
	ds_read2_b64 v[102:105], v210 offset0:100 offset1:102
	v_cvt_pk_bf16_f32 v184, v175, v174
	v_cvt_pk_bf16_f32 v185, v87, v86
	v_cvt_pk_bf16_f32 v182, v98, v99
	v_cvt_pk_bf16_f32 v183, v100, v101
	v_mfma_f32_32x32x16_bf16 v[2:17], v[110:113], v[106:109], v[2:17]
	ds_read2_b64 v[110:113], v209 offset0:72 offset1:74
	ds_read2_b64 v[186:189], v210 offset0:104 offset1:106
	s_waitcnt lgkmcnt(2)
	v_mfma_f32_32x32x16_bf16 v[18:33], v[102:105], v[106:109], v[18:33]
	s_waitcnt lgkmcnt(0)
	v_mfma_f32_32x32x16_bf16 v[2:17], v[110:113], v[182:185], v[2:17]
	v_add_f32_e32 v110, v228, v181
	v_add_f32_e32 v110, v229, v110
	v_add_f32_e32 v110, v219, v110
	v_add_f32_e32 v110, v218, v110
	v_add_f32_e32 v110, v221, v110
	v_add_f32_e32 v110, v220, v110
	v_add_f32_e32 v110, v223, v110
	v_mfma_f32_32x32x16_bf16 v[18:33], v[186:189], v[182:185], v[18:33]
	v_add_f32_e32 v110, v222, v110
	v_add_f32_e32 v97, v97, v110
	v_add_f32_e32 v96, v96, v97
	v_add_f32_e32 v96, v225, v96
	v_add_f32_e32 v96, v224, v96
	v_add_f32_e32 v96, v227, v96
	v_add_f32_e32 v96, v226, v96
	v_mfma_f32_32x32x16_bf16 v[66:81], v[214:217], v[134:137], v[66:81]
	v_add_f32_e32 v203, v180, v96
	v_cvt_pk_bf16_f32 v213, v91, v90
	v_cvt_pk_bf16_f32 v214, v93, v92
	v_cvt_pk_bf16_f32 v215, v95, v94
	ds_read2_b64 v[102:105], v209 offset0:76 offset1:78
	ds_read2_b64 v[106:109], v210 offset0:108 offset1:110
	s_waitcnt lgkmcnt(0)
	v_mfma_f32_32x32x16_bf16 v[2:17], v[102:105], v[212:215], v[2:17]
	v_mfma_f32_32x32x16_bf16 v[18:33], v[106:109], v[212:215], v[18:33]
	s_cbranch_scc0 .Lw47_b800
	s_branch .Lw47_exit

; #define AT_STEPM(C0, C1, MC, N0, N1, MN, t_) do { \
;         AT_WRITEK((t_) + 1); AT_WRITEV(t_); \
;         __syncthreads(); \
;         AT_LOADK((t_) + 2); AT_LOADV((t_) + 1); \
;         AT_SM1(C0, C1, MC, t_, 0); MN = mref; AT_QK(N0, N1, (t_) + 1); AT_SM2(C0, C1, t_); \
;     } while (0)
; #define AT_STEPB(C0, C1, MC, N0, N1, MN, t_) do { \
;         if ((t_) + 1 < NT) AT_WRITEK((t_) + 1); AT_WRITEV(t_); \
;         __syncthreads(); \
;         if ((t_) + 2 < NT) AT_LOADK((t_) + 2); if ((t_) + 1 < NT) AT_LOADV((t_) + 1); \
;         if ((t_) + 1 <= wlim) { MN = mref; AT_QK(N0, N1, (t_) + 1); } \
;         if ((t_) <= wlim) { AT_SM1(C0, C1, MC, t_, 1); AT_SM2(C0, C1, t_); } \
;     } while (0)
; DI void attn_unit(int wv, int h, int qb, const bf16_t* QB, const bf16_t* KB, const bf16_t* VT, bf16_t* MIX, LAS unsigned char* lds) {
;     ...
;     for (; t < 4 * qb; t += 2) {
;         AT_STEPM(pA0, pA1, mA, pB0, pB1, mB, t);
;         AT_STEPM(pB0, pB1, mB, pA0, pA1, mA, t + 1);
;     }
;     for (; t < NT; t += 2) {
;         AT_STEPB(pA0, pA1, mA, pB0, pB1, mB, t);
;         AT_STEPB(pB0, pB1, mB, pA0, pA1, mA, t + 1);
.Lw47_exit:
	s_add_i32 s91, s29, 4
	s_mov_b64 s[8:9], -1
	s_cmp_lt_u32 s12, s91
	v_lshlrev_b32_e32 v158, 2, v178
	s_cbranch_scc1 .LBB0_823
	v_lshlrev_b32_e32 v0, 2, v178
	s_mov_b64 s[8:9], 0
